# v84 + the 12 GEMM K-loop heads aligned to 64-byte instruction fetch lines
# baseline (speedup 1.0000x reference)
;     __device__ __forceinline__ bool next(int i, Unit& u) const { if (i >= n) return false; u.pm = pm; u.pn = pn0 + i; return true; }
;     __device__ __forceinline__ bool next(int i, Unit& u) const { if (i) return false; u.pm = pm; u.pn = pn; return true; }
;     ...
;         const bool has_next = S.next(ui + 1, nxt);
;         const char* nA = has_next ? (const char*)g.A + (size_t)nxt.pm * tstep : cA; const char* nB = has_next ? (const char*)g.Bt + (size_t)nxt.pn * tstep : cB;
;         for (int t = 0; t < nt; t += 2) {
;             const bool last = (t == nt - 2);
;             const char* a1 = cA + (size_t)(t + 1) * kstep;
;             const char* a2 = last ? nA : cA + (size_t)(t + 2) * kstep; const char* b2 = last ? nB : cB + (size_t)(t + 2) * kstep;
;             const char* a3 = a2 + kstep; const char* b3 = b2 + kstep;
;     ...
; #pragma unroll
;         for (int a = 0; a < 2; ++a)
; #pragma unroll
;             for (int b = 0; b < 2; ++b)
; #pragma unroll
;                 for (int m = 0; m < 4; ++m)
; #pragma unroll
;                     for (int n = 0; n < 2; ++n) acc[a][b][m][n] = (f32x4){0.f, 0.f, 0.f, 0.f};
;         cur = nxt; cA = nA; cB = nB; ++ui;
.LBB0_197:
	s_ashr_i32 s25, s24, 31
	s_lshl_b64 s[50:51], s[24:25], 20
	s_add_u32 s50, s36, s50
	s_addc_u32 s51, s37, s51
	s_and_b64 s[58:59], s[4:5], exec
	s_cselect_b32 s25, s51, s61
	s_cselect_b32 s81, s50, s60
	s_ashr_i32 s15, s14, 31
	s_lshl_b64 s[58:59], s[14:15], 20
	s_add_u32 s58, s75, s58
	s_addc_u32 s59, s82, s59
	s_and_b64 s[68:69], s[4:5], exec
	s_cselect_b32 s15, s59, s63
	s_cselect_b32 s83, s58, s62
	s_add_u32 s60, s60, 0x80080
	s_addc_u32 s61, s61, 0
	s_add_u32 s84, s62, 0x100
	v_mov_b32_e32 v4, 0
	s_addc_u32 s85, s63, 0
	s_mov_b32 s86, -2
	v_mov_b32_e32 v5, v4
	v_mov_b32_e32 v6, v4
	v_mov_b32_e32 v7, v4
	v_mov_b32_e32 v8, v4
	v_mov_b32_e32 v9, v4
	v_mov_b32_e32 v10, v4
	v_mov_b32_e32 v11, v4
	v_mov_b32_e32 v20, v4
	v_mov_b32_e32 v21, v4
	v_mov_b32_e32 v22, v4
	v_mov_b32_e32 v23, v4
	s_waitcnt vmcnt(0)
	v_mov_b32_e32 v24, v4
	v_mov_b32_e32 v25, v4
	v_mov_b32_e32 v26, v4
	v_mov_b32_e32 v27, v4
	v_mov_b32_e32 v36, v4
	v_mov_b32_e32 v37, v4
	v_mov_b32_e32 v38, v4
	v_mov_b32_e32 v39, v4
	v_mov_b32_e32 v40, v4
	v_mov_b32_e32 v41, v4
	v_mov_b32_e32 v42, v4
	v_mov_b32_e32 v43, v4
	v_mov_b32_e32 v52, v4
	v_mov_b32_e32 v53, v4
	v_mov_b32_e32 v54, v4
	v_mov_b32_e32 v55, v4
	v_mov_b32_e32 v56, v4
	v_mov_b32_e32 v57, v4
	v_mov_b32_e32 v58, v4
	v_mov_b32_e32 v59, v4
	v_mov_b32_e32 v12, v4
	v_mov_b32_e32 v13, v4
	v_mov_b32_e32 v14, v4
	v_mov_b32_e32 v15, v4
	v_mov_b32_e32 v16, v4
	v_mov_b32_e32 v17, v4
	v_mov_b32_e32 v18, v4
	v_mov_b32_e32 v19, v4
	v_mov_b32_e32 v28, v4
	v_mov_b32_e32 v29, v4
	v_mov_b32_e32 v30, v4
	v_mov_b32_e32 v31, v4
	v_mov_b32_e32 v32, v4
	v_mov_b32_e32 v33, v4
	v_mov_b32_e32 v34, v4
	v_mov_b32_e32 v35, v4
	v_mov_b32_e32 v44, v4
	v_mov_b32_e32 v45, v4
	v_mov_b32_e32 v46, v4
	v_mov_b32_e32 v47, v4
	v_mov_b32_e32 v48, v4
	v_mov_b32_e32 v49, v4
	v_mov_b32_e32 v50, v4
	v_mov_b32_e32 v51, v4
	v_mov_b32_e32 v60, v4
	v_mov_b32_e32 v61, v4
	v_mov_b32_e32 v62, v4
	v_mov_b32_e32 v63, v4
	v_mov_b32_e32 v64, v4
	v_mov_b32_e32 v65, v4
	v_mov_b32_e32 v66, v4
	v_mov_b32_e32 v67, v4
	v_mov_b32_e32 v68, v4
	v_mov_b32_e32 v69, v4
	v_mov_b32_e32 v70, v4
	v_mov_b32_e32 v71, v4
	v_mov_b32_e32 v72, v4
	v_mov_b32_e32 v73, v4
	v_mov_b32_e32 v74, v4
	v_mov_b32_e32 v75, v4
	v_mov_b32_e32 v84, v4
	v_mov_b32_e32 v85, v4
	v_mov_b32_e32 v86, v4
	v_mov_b32_e32 v87, v4
	v_mov_b32_e32 v88, v4
	v_mov_b32_e32 v89, v4
	v_mov_b32_e32 v90, v4
	v_mov_b32_e32 v91, v4
	v_mov_b32_e32 v100, v4
	v_mov_b32_e32 v101, v4
	v_mov_b32_e32 v102, v4
	v_mov_b32_e32 v103, v4
	v_mov_b32_e32 v104, v4
	v_mov_b32_e32 v105, v4
	v_mov_b32_e32 v106, v4
	v_mov_b32_e32 v107, v4
	v_mov_b32_e32 v116, v4
	v_mov_b32_e32 v117, v4
	v_mov_b32_e32 v118, v4
	v_mov_b32_e32 v119, v4
	v_mov_b32_e32 v120, v4
	v_mov_b32_e32 v121, v4
	v_mov_b32_e32 v122, v4
	v_mov_b32_e32 v123, v4
	v_mov_b32_e32 v76, v4
	v_mov_b32_e32 v77, v4
	v_mov_b32_e32 v78, v4
	v_mov_b32_e32 v79, v4
	v_mov_b32_e32 v80, v4
	v_mov_b32_e32 v81, v4
	v_mov_b32_e32 v82, v4
	v_mov_b32_e32 v83, v4
	v_mov_b32_e32 v92, v4
	v_mov_b32_e32 v93, v4
	v_mov_b32_e32 v94, v4
	v_mov_b32_e32 v95, v4
	v_mov_b32_e32 v96, v4
	v_mov_b32_e32 v97, v4
	v_mov_b32_e32 v98, v4
	v_mov_b32_e32 v99, v4
	v_mov_b32_e32 v108, v4
	v_mov_b32_e32 v109, v4
	v_mov_b32_e32 v110, v4
	v_mov_b32_e32 v111, v4
	v_mov_b32_e32 v112, v4
	v_mov_b32_e32 v113, v4
	v_mov_b32_e32 v114, v4
	v_mov_b32_e32 v115, v4
	v_mov_b32_e32 v124, v4
	v_mov_b32_e32 v125, v4
	v_mov_b32_e32 v126, v4
	v_mov_b32_e32 v127, v4
	v_mov_b32_e32 v128, v4
	v_mov_b32_e32 v129, v4
	v_mov_b32_e32 v130, v4
	v_mov_b32_e32 v131, v4
	.p2align	6

;     __device__ __forceinline__ bool next(int i, Unit& u) const { if (i >= n) return false; u.pm = pm; u.pn = pn0 + i; return true; }
;     __device__ __forceinline__ bool next(int i, Unit& u) const { if (i) return false; u.pm = pm; u.pn = pn; return true; }
; #define PG8_STAGE(bufoff, gbase, voff) do { _Pragma("unroll") for (int _i = 0; _i < 2; ++_i) \
;         __builtin_amdgcn_global_load_lds((const unsigned*)((const char*)(gbase) + (voff)[_i]), (PG8_LAS unsigned*)(lds + (bufoff) + ldsw + _i * 8192), 16, 0, 0); } while (0)
; #define PG8_WAIT_V(n) asm volatile("s_waitcnt vmcnt(" #n ")" ::: "memory")
; #define PG8_BAR __builtin_amdgcn_s_barrier()
;     ...
;     for (int i = 0; i < 2; ++i) { int R, C; stage_rc(tid * 16 + i * 8192, R, C); const int Rb = Epi::PERM ? ((R & ~31) + perm32(R & 31)) : R;
;         voffA[i] = (unsigned)(R * K + C) * 2u; voffB[i] = (unsigned)(Rb * K + C) * 2u; }
;     const size_t kstep = (size_t)(BK * 2);
;     const size_t hstep = (size_t)HALF * K * 2;
;     const size_t tstep = 2 * hstep;
;     const unsigned ldsw = (unsigned)wid * 1024u;
;     const int aoff = lds_byte(wr * 64 + fr, fq * 8), boff = lds_byte(wc * 32 + fr, fq * 8);
;     ...
;     Unit cur, nxt; int ui = 0;
;     typename Epi::Pre pre;
;     if (!S.next(0, cur)) return;
;     f32x4 acc[2][2][4][2];
; #pragma unroll
;     for (int a = 0; a < 2; ++a)
; #pragma unroll
;         for (int b = 0; b < 2; ++b)
; #pragma unroll
;             for (int m = 0; m < 4; ++m)
; #pragma unroll
;                 for (int n = 0; n < 2; ++n) acc[a][b][m][n] = (f32x4){0.f, 0.f, 0.f, 0.f};
;     bf16x8 At[4][2], B0[2][2], B1[2][2];
;     const char* cA = (const char*)g.A + (size_t)cur.pm * tstep; const char* cB = (const char*)g.Bt + (size_t)cur.pn * tstep;
;     S.a_ready(cur);
;     if constexpr (SP2) {
;         PG8_STAGE(PG8_SB(0, 0), cB, voffB); PG8_STAGE(PG8_SB(0, 1), cB + hstep, voffB); PG8_STAGE(PG8_SA(0, 0), cA, voffA); PG8_STAGE(PG8_SA(0, 1), cA + hstep, voffA);
;         if (wr == 1) PG8_BAR;
;         PG8_WAIT_V(2); PG8_BAR;
;         PG8_STAGE(PG8_SB(1, 0), cB + kstep, voffB); PG8_STAGE(PG8_SA(1, 0), cA + kstep, voffA); PG8_STAGE(PG8_SB(1, 1), cB + hstep + kstep, voffB);
;         PG8_WAIT_V(6); PG8_BAR;
.LBB0_278:
	v_bfe_u32 v142, v9, 4, 2
	s_and_b32 s25, s6, 3
	v_and_b32_e32 v3, 15, v9
	v_lshlrev_b32_e32 v11, 4, v142
	v_lshlrev_b32_e32 v9, 2, v9
	s_lshl_b32 s24, s7, 6
	v_lshl_or_b32 v11, v3, 6, v11
	v_and_b32_e32 v9, 32, v9
	s_lshl_b32 s6, s7, 13
	s_lshl_b32 s7, s25, 12
	v_bitop3_b32 v143, v11, s7, v9 bitop3:0xde
	v_bitop3_b32 v9, v11, s6, v9 bitop3:0xde
	s_add_u32 s6, s75, 0x400080
	s_addc_u32 s7, s82, 0
	v_mov_b32_e32 v137, v201
	v_mov_b32_e32 v133, v201
	s_add_i32 m0, s15, 0x18000
	v_lshl_add_u64 v[16:17], s[6:7], 0, v[200:201]
	v_lshl_add_u64 v[12:13], s[54:55], 0, v[132:133]
	v_mov_b32_e32 v135, v201
	s_waitcnt vmcnt(2)
	s_barrier
	global_load_lds_dwordx4 v[16:17], off
	v_lshl_add_u64 v[16:17], s[6:7], 0, v[136:137]
	s_add_i32 m0, s15, 0x1a000
	s_add_i32 s42, s15, 0x8000
	s_add_i32 s44, s15, 0xa000
	v_lshl_add_u64 v[14:15], s[54:55], 0, v[134:135]
	global_load_lds_dwordx4 v[16:17], off
	v_lshl_add_u64 v[12:13], v[12:13], 0, s[66:67]
	s_mov_b32 m0, s42
	s_add_u32 s6, s75, 0x480080
	global_load_lds_dwordx4 v[12:13], off
	v_lshl_add_u64 v[12:13], v[14:15], 0, s[66:67]
	s_mov_b32 m0, s44
	s_addc_u32 s7, s82, 0
	global_load_lds_dwordx4 v[12:13], off
	s_add_i32 m0, s15, 0x1c000
	v_lshl_add_u64 v[12:13], s[6:7], 0, v[200:201]
	global_load_lds_dwordx4 v[12:13], off
	v_lshl_add_u64 v[12:13], s[6:7], 0, v[136:137]
	s_add_i32 m0, s15, 0x1e000
	v_lshlrev_b32_e32 v11, 15, v4
	global_load_lds_dwordx4 v[12:13], off
	v_and_b32_e32 v11, 0xffff0000, v11
	v_lshl_add_u32 v5, v5, 12, v11
	v_and_b32_e32 v4, 1, v4
	v_lshl_or_b32 v4, v4, 6, v5
	v_readlane_b32 s6, v255, 14
	v_lshl_add_u32 v4, v6, 1, v4
	v_mov_b32_e32 v5, v201
	v_readlane_b32 s7, v255, 15
	s_add_u32 s0, s28, s0
	s_waitcnt vmcnt(6)
	s_mov_b32 s51, -2
	v_lshl_add_u64 v[138:139], s[6:7], 0, v[4:5]
	v_lshlrev_b32_e32 v4, 15, v7
	v_and_b32_e32 v4, 0xffff0000, v4
	v_lshl_add_u32 v4, v8, 12, v4
	v_and_b32_e32 v5, 1, v7
	v_lshl_or_b32 v4, v5, 6, v4
	v_lshl_add_u32 v4, v10, 1, v4
	v_mov_b32_e32 v5, v201
	v_lshl_add_u64 v[140:141], s[6:7], 0, v[4:5]
	s_addc_u32 s6, s29, 0
	s_add_u32 s0, s0, 0xc00100
	v_mov_b32_e32 v4, 0
	s_addc_u32 s50, s6, 0
	s_mov_b64 s[6:7], 0
	v_add_u32_e32 v144, 0, v9
	v_mov_b32_e32 v5, v4
	v_mov_b32_e32 v6, v4
	v_mov_b32_e32 v7, v4
	v_mov_b32_e32 v8, v4
	v_mov_b32_e32 v9, v4
	v_mov_b32_e32 v10, v4
	v_mov_b32_e32 v11, v4
	v_mov_b32_e32 v20, v4
	v_mov_b32_e32 v21, v4
	v_mov_b32_e32 v22, v4
	v_mov_b32_e32 v23, v4
	v_mov_b32_e32 v24, v4
	v_mov_b32_e32 v25, v4
	v_mov_b32_e32 v26, v4
	v_mov_b32_e32 v27, v4
	v_mov_b32_e32 v36, v4
	v_mov_b32_e32 v37, v4
	v_mov_b32_e32 v38, v4
	v_mov_b32_e32 v39, v4
	v_mov_b32_e32 v40, v4
	v_mov_b32_e32 v41, v4
	v_mov_b32_e32 v42, v4
	v_mov_b32_e32 v43, v4
	v_mov_b32_e32 v52, v4
	v_mov_b32_e32 v53, v4
	v_mov_b32_e32 v54, v4
	v_mov_b32_e32 v55, v4
	v_mov_b32_e32 v56, v4
	v_mov_b32_e32 v57, v4
	v_mov_b32_e32 v58, v4
	v_mov_b32_e32 v59, v4
	v_mov_b32_e32 v12, v4
	v_mov_b32_e32 v13, v4
	v_mov_b32_e32 v14, v4
	v_mov_b32_e32 v15, v4
	v_mov_b32_e32 v16, v4
	v_mov_b32_e32 v17, v4
	v_mov_b32_e32 v18, v4
	v_mov_b32_e32 v19, v4
	v_mov_b32_e32 v28, v4
	v_mov_b32_e32 v29, v4
	v_mov_b32_e32 v30, v4
	v_mov_b32_e32 v31, v4
	v_mov_b32_e32 v32, v4
	v_mov_b32_e32 v33, v4
	v_mov_b32_e32 v34, v4
	v_mov_b32_e32 v35, v4
	v_mov_b32_e32 v44, v4
	v_mov_b32_e32 v45, v4
	v_mov_b32_e32 v46, v4
	v_mov_b32_e32 v47, v4
	v_mov_b32_e32 v48, v4
	v_mov_b32_e32 v49, v4
	v_mov_b32_e32 v50, v4
	v_mov_b32_e32 v51, v4
	v_mov_b32_e32 v60, v4
	v_mov_b32_e32 v61, v4
	v_mov_b32_e32 v62, v4
	v_mov_b32_e32 v63, v4
	v_mov_b32_e32 v64, v4
	v_mov_b32_e32 v65, v4
	v_mov_b32_e32 v66, v4
	v_mov_b32_e32 v67, v4
	v_mov_b32_e32 v68, v4
	v_mov_b32_e32 v69, v4
	v_mov_b32_e32 v70, v4
	v_mov_b32_e32 v71, v4
	v_mov_b32_e32 v72, v4
	v_mov_b32_e32 v73, v4
	v_mov_b32_e32 v74, v4
	v_mov_b32_e32 v75, v4
	v_mov_b32_e32 v84, v4
	v_mov_b32_e32 v85, v4
	v_mov_b32_e32 v86, v4
	v_mov_b32_e32 v87, v4
	v_mov_b32_e32 v88, v4
	v_mov_b32_e32 v89, v4
	v_mov_b32_e32 v90, v4
	v_mov_b32_e32 v91, v4
	v_mov_b32_e32 v100, v4
	v_mov_b32_e32 v101, v4
	v_mov_b32_e32 v102, v4
	v_mov_b32_e32 v103, v4
	v_mov_b32_e32 v104, v4
	v_mov_b32_e32 v105, v4
	v_mov_b32_e32 v106, v4
	v_mov_b32_e32 v107, v4
	v_mov_b32_e32 v116, v4
	v_mov_b32_e32 v117, v4
	v_mov_b32_e32 v118, v4
	v_mov_b32_e32 v119, v4
	v_mov_b32_e32 v120, v4
	v_mov_b32_e32 v121, v4
	v_mov_b32_e32 v122, v4
	v_mov_b32_e32 v123, v4
	v_mov_b32_e32 v76, v4
	v_mov_b32_e32 v77, v4
	v_mov_b32_e32 v78, v4
	v_mov_b32_e32 v79, v4
	v_mov_b32_e32 v80, v4
	v_mov_b32_e32 v81, v4
	v_mov_b32_e32 v82, v4
	v_mov_b32_e32 v83, v4
	v_mov_b32_e32 v92, v4
	v_mov_b32_e32 v93, v4
	v_mov_b32_e32 v94, v4
	v_mov_b32_e32 v95, v4
	v_mov_b32_e32 v96, v4
	v_mov_b32_e32 v97, v4
	v_mov_b32_e32 v98, v4
	v_mov_b32_e32 v99, v4
	v_mov_b32_e32 v108, v4
	v_mov_b32_e32 v109, v4
	v_mov_b32_e32 v110, v4
	v_mov_b32_e32 v111, v4
	v_mov_b32_e32 v112, v4
	v_mov_b32_e32 v113, v4
	v_mov_b32_e32 v114, v4
	v_mov_b32_e32 v115, v4
	v_mov_b32_e32 v124, v4
	v_mov_b32_e32 v125, v4
	v_mov_b32_e32 v126, v4
	v_mov_b32_e32 v127, v4
	v_mov_b32_e32 v128, v4
	v_mov_b32_e32 v129, v4
	v_mov_b32_e32 v130, v4
	v_mov_b32_e32 v131, v4
	s_barrier
	.p2align	6

;     __device__ __forceinline__ bool next(int i, Unit& u) const { if (i >= n) return false; u.pm = pm; u.pn = pn0 + i; return true; }
;     __device__ __forceinline__ bool next(int i, Unit& u) const { if (i) return false; u.pm = pm; u.pn = pn; return true; }
;     ...
;         const bool has_next = S.next(ui + 1, nxt);
;         const char* nA = has_next ? (const char*)g.A + (size_t)nxt.pm * tstep : cA; const char* nB = has_next ? (const char*)g.Bt + (size_t)nxt.pn * tstep : cB;
;     ...
; #pragma unroll
;         for (int a = 0; a < 2; ++a)
; #pragma unroll
;             for (int b = 0; b < 2; ++b)
; #pragma unroll
;                 for (int m = 0; m < 4; ++m)
; #pragma unroll
;                     for (int n = 0; n < 2; ++n) acc[a][b][m][n] = (f32x4){0.f, 0.f, 0.f, 0.f};
;         cur = nxt; cA = nA; cB = nB; ++ui;
.LBB0_289:
	s_add_i32 s62, s63, 1
	s_cmp_lt_u32 s63, 7
	s_mov_b64 s[24:25], s[6:7]
	s_mov_b32 s6, s59
	s_cselect_b64 s[60:61], -1, 0
	s_add_i32 s59, s62, s84
	s_mov_b64 s[50:51], s[4:5]
	s_and_b64 s[4:5], s[60:61], exec
	v_readlane_b32 s5, v254, 23
	s_cselect_b32 s4, s59, s6
	s_cselect_b32 s6, s5, s5
	s_ashr_i32 s7, s6, 31
	s_lshl_b64 s[6:7], s[6:7], 18
	s_add_u32 s6, s78, s6
	s_addc_u32 s7, s79, s7
	s_and_b64 s[68:69], s[60:61], exec
	s_cselect_b32 s68, s7, s25
	s_cselect_b32 s69, s6, s24
	s_ashr_i32 s5, s4, 31
	s_lshl_b64 s[4:5], s[4:5], 18
	s_add_u32 s4, s0, s4
	s_addc_u32 s5, s1, s5
	s_and_b64 s[60:61], s[60:61], exec
	s_cselect_b32 s70, s5, s51
	s_cselect_b32 s71, s4, s50
	s_add_u32 s73, s50, 0x100
	s_addc_u32 s81, s51, 0
	s_add_u32 s24, s24, 0x20080
	v_mov_b32_e32 v4, 0
	s_addc_u32 s25, s25, 0
	s_mov_b32 s83, -2
	v_mov_b32_e32 v5, v4
	v_mov_b32_e32 v6, v4
	v_mov_b32_e32 v7, v4
	v_mov_b32_e32 v8, v4
	v_mov_b32_e32 v9, v4
	v_mov_b32_e32 v10, v4
	v_mov_b32_e32 v11, v4
	v_mov_b32_e32 v20, v4
	v_mov_b32_e32 v21, v4
	v_mov_b32_e32 v22, v4
	v_mov_b32_e32 v23, v4
	v_mov_b32_e32 v24, v4
	v_mov_b32_e32 v25, v4
	v_mov_b32_e32 v26, v4
	v_mov_b32_e32 v27, v4
	v_mov_b32_e32 v36, v4
	v_mov_b32_e32 v37, v4
	v_mov_b32_e32 v38, v4
	v_mov_b32_e32 v39, v4
	v_mov_b32_e32 v40, v4
	v_mov_b32_e32 v41, v4
	v_mov_b32_e32 v42, v4
	v_mov_b32_e32 v43, v4
	v_mov_b32_e32 v52, v4
	v_mov_b32_e32 v53, v4
	v_mov_b32_e32 v54, v4
	v_mov_b32_e32 v55, v4
	v_mov_b32_e32 v56, v4
	v_mov_b32_e32 v57, v4
	v_mov_b32_e32 v58, v4
	v_mov_b32_e32 v59, v4
	v_mov_b32_e32 v12, v4
	v_mov_b32_e32 v13, v4
	v_mov_b32_e32 v14, v4
	v_mov_b32_e32 v15, v4
	v_mov_b32_e32 v16, v4
	v_mov_b32_e32 v17, v4
	v_mov_b32_e32 v18, v4
	v_mov_b32_e32 v19, v4
	v_mov_b32_e32 v28, v4
	v_mov_b32_e32 v29, v4
	v_mov_b32_e32 v30, v4
	v_mov_b32_e32 v31, v4
	v_mov_b32_e32 v32, v4
	v_mov_b32_e32 v33, v4
	v_mov_b32_e32 v34, v4
	v_mov_b32_e32 v35, v4
	v_mov_b32_e32 v44, v4
	v_mov_b32_e32 v45, v4
	v_mov_b32_e32 v46, v4
	v_mov_b32_e32 v47, v4
	v_mov_b32_e32 v48, v4
	v_mov_b32_e32 v49, v4
	v_mov_b32_e32 v50, v4
	v_mov_b32_e32 v51, v4
	v_mov_b32_e32 v60, v4
	v_mov_b32_e32 v61, v4
	v_mov_b32_e32 v62, v4
	v_mov_b32_e32 v63, v4
	v_mov_b32_e32 v64, v4
	v_mov_b32_e32 v65, v4
	v_mov_b32_e32 v66, v4
	v_mov_b32_e32 v67, v4
	v_mov_b32_e32 v68, v4
	v_mov_b32_e32 v69, v4
	v_mov_b32_e32 v70, v4
	v_mov_b32_e32 v71, v4
	v_mov_b32_e32 v72, v4
	v_mov_b32_e32 v73, v4
	v_mov_b32_e32 v74, v4
	v_mov_b32_e32 v75, v4
	v_mov_b32_e32 v84, v4
	v_mov_b32_e32 v85, v4
	v_mov_b32_e32 v86, v4
	v_mov_b32_e32 v87, v4
	v_mov_b32_e32 v88, v4
	v_mov_b32_e32 v89, v4
	v_mov_b32_e32 v90, v4
	v_mov_b32_e32 v91, v4
	v_mov_b32_e32 v100, v4
	v_mov_b32_e32 v101, v4
	v_mov_b32_e32 v102, v4
	v_mov_b32_e32 v103, v4
	v_mov_b32_e32 v104, v4
	v_mov_b32_e32 v105, v4
	v_mov_b32_e32 v106, v4
	v_mov_b32_e32 v107, v4
	v_mov_b32_e32 v116, v4
	v_mov_b32_e32 v117, v4
	v_mov_b32_e32 v118, v4
	v_mov_b32_e32 v119, v4
	v_mov_b32_e32 v120, v4
	v_mov_b32_e32 v121, v4
	v_mov_b32_e32 v122, v4
	v_mov_b32_e32 v123, v4
	v_mov_b32_e32 v76, v4
	v_mov_b32_e32 v77, v4
	v_mov_b32_e32 v78, v4
	v_mov_b32_e32 v79, v4
	v_mov_b32_e32 v80, v4
	v_mov_b32_e32 v81, v4
	v_mov_b32_e32 v82, v4
	v_mov_b32_e32 v83, v4
	v_mov_b32_e32 v92, v4
	v_mov_b32_e32 v93, v4
	v_mov_b32_e32 v94, v4
	v_mov_b32_e32 v95, v4
	v_mov_b32_e32 v96, v4
	v_mov_b32_e32 v97, v4
	v_mov_b32_e32 v98, v4
	v_mov_b32_e32 v99, v4
	v_mov_b32_e32 v108, v4
	v_mov_b32_e32 v109, v4
	v_mov_b32_e32 v110, v4
	v_mov_b32_e32 v111, v4
	v_mov_b32_e32 v112, v4
	v_mov_b32_e32 v113, v4
	v_mov_b32_e32 v114, v4
	v_mov_b32_e32 v115, v4
	v_mov_b32_e32 v124, v4
	v_mov_b32_e32 v125, v4
	v_mov_b32_e32 v126, v4
	v_mov_b32_e32 v127, v4
	v_mov_b32_e32 v128, v4
	v_mov_b32_e32 v129, v4
	v_mov_b32_e32 v130, v4
	v_mov_b32_e32 v131, v4
	.p2align	6

;     __device__ __forceinline__ bool next(int i, Unit& u) const { if (i >= n) return false; u.pm = pm; u.pn = pn0 + i; return true; }
;     __device__ __forceinline__ bool next(int i, Unit& u) const { if (i) return false; u.pm = pm; u.pn = pn; return true; }
;     ...
;         const bool has_next = S.next(ui + 1, nxt);
;         const char* nA = has_next ? (const char*)g.A + (size_t)nxt.pm * tstep : cA; const char* nB = has_next ? (const char*)g.Bt + (size_t)nxt.pn * tstep : cB;
;     ...
; #pragma unroll
;         for (int a = 0; a < 2; ++a)
; #pragma unroll
;             for (int b = 0; b < 2; ++b)
; #pragma unroll
;                 for (int m = 0; m < 4; ++m)
; #pragma unroll
;                     for (int n = 0; n < 2; ++n) acc[a][b][m][n] = (f32x4){0.f, 0.f, 0.f, 0.f};
;         cur = nxt; cA = nA; cB = nB; ++ui;
.LBB0_300:
	s_mov_b32 s20, s79
	s_add_i32 s79, s79, 1
	s_mov_b64 s[24:25], s[4:5]
	s_cmp_lt_u32 s79, s21
	v_readlane_b32 s4, v254, 30
	s_mov_b64 s[14:15], s[6:7]
	s_mov_b32 s6, s83
	s_cselect_b64 s[50:51], -1, 0
	s_add_i32 s83, s79, s4
	s_and_b64 s[4:5], s[50:51], exec
	v_readlane_b32 s5, v254, 23
	s_cselect_b32 s4, s83, s6
	s_cselect_b32 s6, s5, s5
	s_ashr_i32 s7, s6, 31
	s_lshl_b64 s[6:7], s[6:7], 18
	s_add_u32 s6, s76, s6
	s_addc_u32 s7, s77, s7
	s_and_b64 s[52:53], s[50:51], exec
	s_cselect_b32 s21, s7, s15
	s_cselect_b32 s23, s6, s14
	s_ashr_i32 s5, s4, 31
	s_lshl_b64 s[4:5], s[4:5], 18
	s_add_u32 s4, s58, s4
	s_addc_u32 s5, s59, s5
	s_and_b64 s[50:51], s[50:51], exec
	s_cselect_b32 s42, s5, s25
	s_cselect_b32 s44, s4, s24
	s_add_u32 s52, s24, 0x100
	s_addc_u32 s53, s25, 0
	s_add_u32 s14, s14, 0x20080
	v_mov_b32_e32 v4, 0
	s_addc_u32 s15, s15, 0
	s_mov_b32 s54, -2
	v_mov_b32_e32 v5, v4
	v_mov_b32_e32 v6, v4
	v_mov_b32_e32 v7, v4
	v_mov_b32_e32 v8, v4
	v_mov_b32_e32 v9, v4
	v_mov_b32_e32 v10, v4
	v_mov_b32_e32 v11, v4
	v_mov_b32_e32 v16, v4
	v_mov_b32_e32 v17, v4
	v_mov_b32_e32 v18, v4
	v_mov_b32_e32 v19, v4
	v_mov_b32_e32 v24, v4
	v_mov_b32_e32 v25, v4
	v_mov_b32_e32 v26, v4
	v_mov_b32_e32 v27, v4
	v_mov_b32_e32 v32, v4
	v_mov_b32_e32 v33, v4
	v_mov_b32_e32 v34, v4
	v_mov_b32_e32 v35, v4
	v_mov_b32_e32 v40, v4
	v_mov_b32_e32 v41, v4
	v_mov_b32_e32 v42, v4
	v_mov_b32_e32 v43, v4
	v_mov_b32_e32 v48, v4
	v_mov_b32_e32 v49, v4
	v_mov_b32_e32 v50, v4
	v_mov_b32_e32 v51, v4
	v_mov_b32_e32 v56, v4
	v_mov_b32_e32 v57, v4
	v_mov_b32_e32 v58, v4
	v_mov_b32_e32 v59, v4
	v_mov_b32_e32 v12, v4
	v_mov_b32_e32 v13, v4
	v_mov_b32_e32 v14, v4
	v_mov_b32_e32 v15, v4
	v_mov_b32_e32 v20, v4
	v_mov_b32_e32 v21, v4
	v_mov_b32_e32 v22, v4
	v_mov_b32_e32 v23, v4
	v_mov_b32_e32 v28, v4
	v_mov_b32_e32 v29, v4
	v_mov_b32_e32 v30, v4
	v_mov_b32_e32 v31, v4
	v_mov_b32_e32 v36, v4
	v_mov_b32_e32 v37, v4
	v_mov_b32_e32 v38, v4
	v_mov_b32_e32 v39, v4
	v_mov_b32_e32 v44, v4
	v_mov_b32_e32 v45, v4
	v_mov_b32_e32 v46, v4
	v_mov_b32_e32 v47, v4
	v_mov_b32_e32 v52, v4
	v_mov_b32_e32 v53, v4
	v_mov_b32_e32 v54, v4
	v_mov_b32_e32 v55, v4
	v_mov_b32_e32 v60, v4
	v_mov_b32_e32 v61, v4
	v_mov_b32_e32 v62, v4
	v_mov_b32_e32 v63, v4
	v_mov_b32_e32 v64, v4
	v_mov_b32_e32 v65, v4
	v_mov_b32_e32 v66, v4
	v_mov_b32_e32 v67, v4
	v_mov_b32_e32 v68, v4
	v_mov_b32_e32 v69, v4
	v_mov_b32_e32 v70, v4
	v_mov_b32_e32 v71, v4
	v_mov_b32_e32 v72, v4
	v_mov_b32_e32 v73, v4
	v_mov_b32_e32 v74, v4
	v_mov_b32_e32 v75, v4
	v_mov_b32_e32 v80, v4
	v_mov_b32_e32 v81, v4
	v_mov_b32_e32 v82, v4
	v_mov_b32_e32 v83, v4
	v_mov_b32_e32 v88, v4
	v_mov_b32_e32 v89, v4
	v_mov_b32_e32 v90, v4
	v_mov_b32_e32 v91, v4
	v_mov_b32_e32 v96, v4
	v_mov_b32_e32 v97, v4
	v_mov_b32_e32 v98, v4
	v_mov_b32_e32 v99, v4
	v_mov_b32_e32 v104, v4
	v_mov_b32_e32 v105, v4
	v_mov_b32_e32 v106, v4
	v_mov_b32_e32 v107, v4
	v_mov_b32_e32 v112, v4
	v_mov_b32_e32 v113, v4
	v_mov_b32_e32 v114, v4
	v_mov_b32_e32 v115, v4
	v_mov_b32_e32 v120, v4
	v_mov_b32_e32 v121, v4
	v_mov_b32_e32 v122, v4
	v_mov_b32_e32 v123, v4
	v_mov_b32_e32 v76, v4
	v_mov_b32_e32 v77, v4
	v_mov_b32_e32 v78, v4
	v_mov_b32_e32 v79, v4
	v_mov_b32_e32 v84, v4
	v_mov_b32_e32 v85, v4
	v_mov_b32_e32 v86, v4
	v_mov_b32_e32 v87, v4
	v_mov_b32_e32 v92, v4
	v_mov_b32_e32 v93, v4
	v_mov_b32_e32 v94, v4
	v_mov_b32_e32 v95, v4
	v_mov_b32_e32 v100, v4
	v_mov_b32_e32 v101, v4
	v_mov_b32_e32 v102, v4
	v_mov_b32_e32 v103, v4
	v_mov_b32_e32 v108, v4
	v_mov_b32_e32 v109, v4
	v_mov_b32_e32 v110, v4
	v_mov_b32_e32 v111, v4
	v_mov_b32_e32 v116, v4
	v_mov_b32_e32 v117, v4
	v_mov_b32_e32 v118, v4
	v_mov_b32_e32 v119, v4
	v_mov_b32_e32 v124, v4
	v_mov_b32_e32 v125, v4
	v_mov_b32_e32 v126, v4
	v_mov_b32_e32 v127, v4
	v_mov_b32_e32 v128, v4
	v_mov_b32_e32 v129, v4
	v_mov_b32_e32 v130, v4
	v_mov_b32_e32 v131, v4
	s_waitcnt lgkmcnt(0)
	.p2align	6

;     __device__ __forceinline__ bool next(int i, Unit& u) const { if (i >= n) return false; u.pm = pm; u.pn = pn0 + i; return true; }
;     __device__ __forceinline__ bool next(int i, Unit& u) const { if (i) return false; u.pm = pm; u.pn = pn; return true; }
;     ...
;         const bool has_next = S.next(ui + 1, nxt);
;         const char* nA = has_next ? (const char*)g.A + (size_t)nxt.pm * tstep : cA; const char* nB = has_next ? (const char*)g.Bt + (size_t)nxt.pn * tstep : cB;
;         for (int t = 0; t < nt; t += 2) {
;             const bool last = (t == nt - 2);
;             const char* a1 = cA + (size_t)(t + 1) * kstep;
;             const char* a2 = last ? nA : cA + (size_t)(t + 2) * kstep; const char* b2 = last ? nB : cB + (size_t)(t + 2) * kstep;
;             const char* a3 = a2 + kstep; const char* b3 = b2 + kstep;
;     ...
; #pragma unroll
;         for (int a = 0; a < 2; ++a)
; #pragma unroll
;             for (int b = 0; b < 2; ++b)
; #pragma unroll
;                 for (int m = 0; m < 4; ++m)
; #pragma unroll
;                     for (int n = 0; n < 2; ++n) acc[a][b][m][n] = (f32x4){0.f, 0.f, 0.f, 0.f};
;         cur = nxt; cA = nA; cB = nB; ++ui;
.LBB0_453:
	s_ashr_i32 s25, s24, 31
	s_lshl_b64 s[50:51], s[24:25], 20
	s_add_u32 s50, s58, s50
	s_addc_u32 s51, s59, s51
	s_and_b64 s[60:61], s[6:7], exec
	s_cselect_b32 s25, s51, s69
	s_cselect_b32 s76, s50, s68
	s_ashr_i32 s15, s14, 31
	s_lshl_b64 s[60:61], s[14:15], 20
	s_add_u32 s60, s1, s60
	s_addc_u32 s61, s4, s61
	s_and_b64 s[70:71], s[6:7], exec
	s_cselect_b32 s15, s61, s63
	s_cselect_b32 s77, s60, s62
	s_add_u32 s78, s62, 0x100
	s_addc_u32 s79, s63, 0
	s_add_u32 s62, s68, 0x80080
	v_mov_b32_e32 v4, 0
	s_addc_u32 s63, s69, 0
	s_mov_b32 s81, -2
	v_mov_b32_e32 v5, v4
	v_mov_b32_e32 v6, v4
	v_mov_b32_e32 v7, v4
	v_mov_b32_e32 v8, v4
	v_mov_b32_e32 v9, v4
	v_mov_b32_e32 v10, v4
	v_mov_b32_e32 v11, v4
	v_mov_b32_e32 v20, v4
	v_mov_b32_e32 v21, v4
	v_mov_b32_e32 v22, v4
	v_mov_b32_e32 v23, v4
	v_mov_b32_e32 v24, v4
	v_mov_b32_e32 v25, v4
	v_mov_b32_e32 v26, v4
	v_mov_b32_e32 v27, v4
	v_mov_b32_e32 v36, v4
	v_mov_b32_e32 v37, v4
	v_mov_b32_e32 v38, v4
	v_mov_b32_e32 v39, v4
	v_mov_b32_e32 v40, v4
	v_mov_b32_e32 v41, v4
	v_mov_b32_e32 v42, v4
	v_mov_b32_e32 v43, v4
	v_mov_b32_e32 v52, v4
	v_mov_b32_e32 v53, v4
	v_mov_b32_e32 v54, v4
	v_mov_b32_e32 v55, v4
	v_mov_b32_e32 v56, v4
	v_mov_b32_e32 v57, v4
	v_mov_b32_e32 v58, v4
	v_mov_b32_e32 v59, v4
	v_mov_b32_e32 v12, v4
	v_mov_b32_e32 v13, v4
	v_mov_b32_e32 v14, v4
	v_mov_b32_e32 v15, v4
	v_mov_b32_e32 v16, v4
	v_mov_b32_e32 v17, v4
	v_mov_b32_e32 v18, v4
	v_mov_b32_e32 v19, v4
	v_mov_b32_e32 v28, v4
	v_mov_b32_e32 v29, v4
	v_mov_b32_e32 v30, v4
	v_mov_b32_e32 v31, v4
	v_mov_b32_e32 v32, v4
	v_mov_b32_e32 v33, v4
	v_mov_b32_e32 v34, v4
	v_mov_b32_e32 v35, v4
	v_mov_b32_e32 v44, v4
	v_mov_b32_e32 v45, v4
	v_mov_b32_e32 v46, v4
	v_mov_b32_e32 v47, v4
	v_mov_b32_e32 v48, v4
	v_mov_b32_e32 v49, v4
	v_mov_b32_e32 v50, v4
	v_mov_b32_e32 v51, v4
	v_mov_b32_e32 v60, v4
	v_mov_b32_e32 v61, v4
	v_mov_b32_e32 v62, v4
	v_mov_b32_e32 v63, v4
	v_mov_b32_e32 v64, v4
	v_mov_b32_e32 v65, v4
	v_mov_b32_e32 v66, v4
	v_mov_b32_e32 v67, v4
	v_mov_b32_e32 v68, v4
	v_mov_b32_e32 v69, v4
	v_mov_b32_e32 v70, v4
	v_mov_b32_e32 v71, v4
	v_mov_b32_e32 v72, v4
	v_mov_b32_e32 v73, v4
	v_mov_b32_e32 v74, v4
	v_mov_b32_e32 v75, v4
	v_mov_b32_e32 v84, v4
	v_mov_b32_e32 v85, v4
	v_mov_b32_e32 v86, v4
	v_mov_b32_e32 v87, v4
	v_mov_b32_e32 v88, v4
	v_mov_b32_e32 v89, v4
	v_mov_b32_e32 v90, v4
	v_mov_b32_e32 v91, v4
	v_mov_b32_e32 v100, v4
	v_mov_b32_e32 v101, v4
	v_mov_b32_e32 v102, v4
	v_mov_b32_e32 v103, v4
	v_mov_b32_e32 v104, v4
	v_mov_b32_e32 v105, v4
	v_mov_b32_e32 v106, v4
	v_mov_b32_e32 v107, v4
	v_mov_b32_e32 v124, v4
	v_mov_b32_e32 v125, v4
	v_mov_b32_e32 v126, v4
	v_mov_b32_e32 v127, v4
	v_mov_b32_e32 v132, v4
	v_mov_b32_e32 v133, v4
	v_mov_b32_e32 v134, v4
	v_mov_b32_e32 v135, v4
	v_mov_b32_e32 v76, v4
	v_mov_b32_e32 v77, v4
	v_mov_b32_e32 v78, v4
	v_mov_b32_e32 v79, v4
	v_mov_b32_e32 v80, v4
	v_mov_b32_e32 v81, v4
	v_mov_b32_e32 v82, v4
	v_mov_b32_e32 v83, v4
	v_mov_b32_e32 v92, v4
	v_mov_b32_e32 v93, v4
	v_mov_b32_e32 v94, v4
	v_mov_b32_e32 v95, v4
	v_mov_b32_e32 v96, v4
	v_mov_b32_e32 v97, v4
	v_mov_b32_e32 v98, v4
	v_mov_b32_e32 v99, v4
	v_mov_b32_e32 v116, v4
	v_mov_b32_e32 v117, v4
	v_mov_b32_e32 v118, v4
	v_mov_b32_e32 v119, v4
	v_mov_b32_e32 v120, v4
	v_mov_b32_e32 v121, v4
	v_mov_b32_e32 v122, v4
	v_mov_b32_e32 v123, v4
	v_mov_b32_e32 v140, v4
	v_mov_b32_e32 v141, v4
	v_mov_b32_e32 v142, v4
	v_mov_b32_e32 v143, v4
	v_mov_b32_e32 v144, v4
	v_mov_b32_e32 v145, v4
	v_mov_b32_e32 v146, v4
	v_mov_b32_e32 v147, v4
	.p2align	6

;     __device__ __forceinline__ bool next(int i, Unit& u) const { if (i >= n) return false; u.pm = pm; u.pn = pn0 + i; return true; }
;     __device__ __forceinline__ bool next(int i, Unit& u) const { if (i) return false; u.pm = pm; u.pn = pn; return true; }
;     ...
;         const bool has_next = S.next(ui + 1, nxt);
;         const char* nA = has_next ? (const char*)g.A + (size_t)nxt.pm * tstep : cA; const char* nB = has_next ? (const char*)g.Bt + (size_t)nxt.pn * tstep : cB;
;         for (int t = 0; t < nt; t += 2) {
;             const bool last = (t == nt - 2);
;             const char* a1 = cA + (size_t)(t + 1) * kstep;
;             const char* a2 = last ? nA : cA + (size_t)(t + 2) * kstep; const char* b2 = last ? nB : cB + (size_t)(t + 2) * kstep;
;             const char* a3 = a2 + kstep; const char* b3 = b2 + kstep;
;     ...
; #pragma unroll
;         for (int a = 0; a < 2; ++a)
; #pragma unroll
;             for (int b = 0; b < 2; ++b)
; #pragma unroll
;                 for (int m = 0; m < 4; ++m)
; #pragma unroll
;                     for (int n = 0; n < 2; ++n) acc[a][b][m][n] = (f32x4){0.f, 0.f, 0.f, 0.f};
;         cur = nxt; cA = nA; cB = nB; ++ui;
.LBB0_541:
	s_ashr_i32 s25, s24, 31
	s_lshl_b64 s[14:15], s[24:25], 20
	s_add_u32 s90, s36, s14
	s_addc_u32 s91, s37, s15
	s_and_b64 s[14:15], s[8:9], exec
	s_cselect_b32 s25, s91, s11
	s_cselect_b32 s69, s90, s10
	s_ashr_i32 s89, s88, 31
	s_lshl_b64 s[14:15], s[88:89], 20
	s_add_u32 s94, s6, s14
	s_addc_u32 s95, s7, s15
	s_and_b64 s[14:15], s[8:9], exec
	s_cselect_b32 s76, s95, s13
	s_cselect_b32 s77, s94, s12
	s_add_u32 s10, s10, 0x80080
	s_addc_u32 s11, s11, 0
	s_add_u32 s82, s12, 0x100
	v_mov_b32_e32 v12, 0
	s_addc_u32 s83, s13, 0
	s_mov_b32 s89, -2
	v_mov_b32_e32 v13, v12
	v_mov_b32_e32 v14, v12
	v_mov_b32_e32 v15, v12
	v_mov_b32_e32 v16, v12
	v_mov_b32_e32 v17, v12
	v_mov_b32_e32 v18, v12
	v_mov_b32_e32 v19, v12
	v_mov_b32_e32 v24, v12
	v_mov_b32_e32 v25, v12
	v_mov_b32_e32 v26, v12
	v_mov_b32_e32 v27, v12
	v_mov_b32_e32 v84, v12
	v_mov_b32_e32 v85, v12
	v_mov_b32_e32 v86, v12
	v_mov_b32_e32 v87, v12
	v_mov_b32_e32 v28, v12
	v_mov_b32_e32 v29, v12
	v_mov_b32_e32 v30, v12
	v_mov_b32_e32 v31, v12
	v_mov_b32_e32 v88, v12
	v_mov_b32_e32 v89, v12
	v_mov_b32_e32 v90, v12
	v_mov_b32_e32 v91, v12
	v_mov_b32_e32 v32, v12
	v_mov_b32_e32 v33, v12
	v_mov_b32_e32 v34, v12
	v_mov_b32_e32 v35, v12
	v_mov_b32_e32 v102, v12
	v_mov_b32_e32 v103, v12
	v_mov_b32_e32 v104, v12
	v_mov_b32_e32 v105, v12
	v_mov_b32_e32 v20, v12
	v_mov_b32_e32 v21, v12
	v_mov_b32_e32 v22, v12
	v_mov_b32_e32 v23, v12
	v_mov_b32_e32 v80, v12
	v_mov_b32_e32 v81, v12
	v_mov_b32_e32 v82, v12
	v_mov_b32_e32 v83, v12
	v_mov_b32_e32 v36, v12
	v_mov_b32_e32 v37, v12
	v_mov_b32_e32 v38, v12
	v_mov_b32_e32 v39, v12
	v_mov_b32_e32 v138, v12
	v_mov_b32_e32 v139, v12
	v_mov_b32_e32 v140, v12
	v_mov_b32_e32 v141, v12
	v_mov_b32_e32 v40, v12
	v_mov_b32_e32 v41, v12
	v_mov_b32_e32 v42, v12
	v_mov_b32_e32 v43, v12
	v_mov_b32_e32 v142, v12
	v_mov_b32_e32 v143, v12
	v_mov_b32_e32 v144, v12
	v_mov_b32_e32 v145, v12
	v_mov_b32_e32 v44, v12
	v_mov_b32_e32 v45, v12
	v_mov_b32_e32 v46, v12
	v_mov_b32_e32 v47, v12
	v_mov_b32_e32 v146, v12
	v_mov_b32_e32 v147, v12
	v_mov_b32_e32 v148, v12
	v_mov_b32_e32 v149, v12
	v_mov_b32_e32 v68, v12
	v_mov_b32_e32 v69, v12
	v_mov_b32_e32 v70, v12
	v_mov_b32_e32 v71, v12
	v_mov_b32_e32 v92, v12
	v_mov_b32_e32 v93, v12
	v_mov_b32_e32 v94, v12
	v_mov_b32_e32 v95, v12
	v_mov_b32_e32 v48, v12
	v_mov_b32_e32 v49, v12
	v_mov_b32_e32 v50, v12
	v_mov_b32_e32 v51, v12
	v_mov_b32_e32 v150, v12
	v_mov_b32_e32 v151, v12
	v_mov_b32_e32 v152, v12
	v_mov_b32_e32 v153, v12
	v_mov_b32_e32 v52, v12
	v_mov_b32_e32 v53, v12
	v_mov_b32_e32 v54, v12
	v_mov_b32_e32 v55, v12
	v_mov_b32_e32 v154, v12
	v_mov_b32_e32 v155, v12
	v_mov_b32_e32 v156, v12
	v_mov_b32_e32 v157, v12
	v_mov_b32_e32 v64, v12
	v_mov_b32_e32 v65, v12
	v_mov_b32_e32 v66, v12
	v_mov_b32_e32 v67, v12
	v_mov_b32_e32 v8, v12
	v_mov_b32_e32 v9, v12
	v_mov_b32_e32 v10, v12
	v_mov_b32_e32 v11, v12
	v_mov_b32_e32 v76, v12
	v_mov_b32_e32 v77, v12
	v_mov_b32_e32 v78, v12
	v_mov_b32_e32 v79, v12
	v_mov_b32_e32 v96, v12
	v_mov_b32_e32 v97, v12
	v_mov_b32_e32 v98, v12
	v_mov_b32_e32 v99, v12
	v_mov_b32_e32 v56, v12
	v_mov_b32_e32 v57, v12
	v_mov_b32_e32 v58, v12
	v_mov_b32_e32 v59, v12
	v_mov_b32_e32 v158, v12
	v_mov_b32_e32 v159, v12
	v_mov_b32_e32 v160, v12
	v_mov_b32_e32 v161, v12
	v_mov_b32_e32 v60, v12
	v_mov_b32_e32 v61, v12
	v_mov_b32_e32 v62, v12
	v_mov_b32_e32 v63, v12
	v_mov_b32_e32 v162, v12
	v_mov_b32_e32 v163, v12
	v_mov_b32_e32 v164, v12
	v_mov_b32_e32 v165, v12
	v_mov_b32_e32 v72, v12
	v_mov_b32_e32 v73, v12
	v_mov_b32_e32 v74, v12
	v_mov_b32_e32 v75, v12
	v_mov_b32_e32 v4, v12
	v_mov_b32_e32 v5, v12
	v_mov_b32_e32 v6, v12
	v_mov_b32_e32 v7, v12
	.p2align	6

;     ...
; #pragma unroll
;         for (int a = 0; a < 2; ++a)
; #pragma unroll
;             for (int b = 0; b < 2; ++b)
; #pragma unroll
;                 for (int m = 0; m < 4; ++m)
; #pragma unroll
;                     for (int n = 0; n < 2; ++n) acc[a][b][m][n] = (f32x4){0.f, 0.f, 0.f, 0.f};
;         cur = nxt; cA = nA; cB = nB; ++ui;
.LBB0_666:
	s_add_u32 s73, s68, 0x100
	v_mov_b32_e32 v4, 0
	s_addc_u32 s75, s69, 0
	s_mov_b32 s78, -2
	v_mov_b32_e32 v5, v4
	v_mov_b32_e32 v6, v4
	v_mov_b32_e32 v7, v4
	v_mov_b32_e32 v8, v4
	v_mov_b32_e32 v9, v4
	v_mov_b32_e32 v10, v4
	v_mov_b32_e32 v11, v4
	v_mov_b32_e32 v20, v4
	v_mov_b32_e32 v21, v4
	v_mov_b32_e32 v22, v4
	v_mov_b32_e32 v23, v4
	s_waitcnt vmcnt(0)
	v_mov_b32_e32 v24, v4
	v_mov_b32_e32 v25, v4
	v_mov_b32_e32 v26, v4
	v_mov_b32_e32 v27, v4
	v_mov_b32_e32 v36, v4
	v_mov_b32_e32 v37, v4
	v_mov_b32_e32 v38, v4
	v_mov_b32_e32 v39, v4
	v_mov_b32_e32 v40, v4
	v_mov_b32_e32 v41, v4
	v_mov_b32_e32 v42, v4
	v_mov_b32_e32 v43, v4
	v_mov_b32_e32 v52, v4
	v_mov_b32_e32 v53, v4
	v_mov_b32_e32 v54, v4
	v_mov_b32_e32 v55, v4
	v_mov_b32_e32 v56, v4
	v_mov_b32_e32 v57, v4
	v_mov_b32_e32 v58, v4
	v_mov_b32_e32 v59, v4
	v_mov_b32_e32 v12, v4
	v_mov_b32_e32 v13, v4
	v_mov_b32_e32 v14, v4
	v_mov_b32_e32 v15, v4
	v_mov_b32_e32 v16, v4
	v_mov_b32_e32 v17, v4
	v_mov_b32_e32 v18, v4
	v_mov_b32_e32 v19, v4
	v_mov_b32_e32 v28, v4
	v_mov_b32_e32 v29, v4
	v_mov_b32_e32 v30, v4
	v_mov_b32_e32 v31, v4
	v_mov_b32_e32 v32, v4
	v_mov_b32_e32 v33, v4
	v_mov_b32_e32 v34, v4
	v_mov_b32_e32 v35, v4
	v_mov_b32_e32 v44, v4
	v_mov_b32_e32 v45, v4
	v_mov_b32_e32 v46, v4
	v_mov_b32_e32 v47, v4
	v_mov_b32_e32 v48, v4
	v_mov_b32_e32 v49, v4
	v_mov_b32_e32 v50, v4
	v_mov_b32_e32 v51, v4
	v_mov_b32_e32 v60, v4
	v_mov_b32_e32 v61, v4
	v_mov_b32_e32 v62, v4
	v_mov_b32_e32 v63, v4
	v_mov_b32_e32 v64, v4
	v_mov_b32_e32 v65, v4
	v_mov_b32_e32 v66, v4
	v_mov_b32_e32 v67, v4
	v_mov_b32_e32 v68, v4
	v_mov_b32_e32 v69, v4
	v_mov_b32_e32 v70, v4
	v_mov_b32_e32 v71, v4
	v_mov_b32_e32 v72, v4
	v_mov_b32_e32 v73, v4
	v_mov_b32_e32 v74, v4
	v_mov_b32_e32 v75, v4
	v_mov_b32_e32 v84, v4
	v_mov_b32_e32 v85, v4
	v_mov_b32_e32 v86, v4
	v_mov_b32_e32 v87, v4
	v_mov_b32_e32 v88, v4
	v_mov_b32_e32 v89, v4
	v_mov_b32_e32 v90, v4
	v_mov_b32_e32 v91, v4
	v_mov_b32_e32 v100, v4
	v_mov_b32_e32 v101, v4
	v_mov_b32_e32 v102, v4
	v_mov_b32_e32 v103, v4
	v_mov_b32_e32 v104, v4
	v_mov_b32_e32 v105, v4
	v_mov_b32_e32 v106, v4
	v_mov_b32_e32 v107, v4
	v_mov_b32_e32 v124, v4
	v_mov_b32_e32 v125, v4
	v_mov_b32_e32 v126, v4
	v_mov_b32_e32 v127, v4
	v_mov_b32_e32 v132, v4
	v_mov_b32_e32 v133, v4
	v_mov_b32_e32 v134, v4
	v_mov_b32_e32 v135, v4
	v_mov_b32_e32 v76, v4
	v_mov_b32_e32 v77, v4
	v_mov_b32_e32 v78, v4
	v_mov_b32_e32 v79, v4
	v_mov_b32_e32 v80, v4
	v_mov_b32_e32 v81, v4
	v_mov_b32_e32 v82, v4
	v_mov_b32_e32 v83, v4
	v_mov_b32_e32 v92, v4
	v_mov_b32_e32 v93, v4
	v_mov_b32_e32 v94, v4
	v_mov_b32_e32 v95, v4
	v_mov_b32_e32 v96, v4
	v_mov_b32_e32 v97, v4
	v_mov_b32_e32 v98, v4
	v_mov_b32_e32 v99, v4
	v_mov_b32_e32 v116, v4
	v_mov_b32_e32 v117, v4
	v_mov_b32_e32 v118, v4
	v_mov_b32_e32 v119, v4
	v_mov_b32_e32 v120, v4
	v_mov_b32_e32 v121, v4
	v_mov_b32_e32 v122, v4
	v_mov_b32_e32 v123, v4
	v_mov_b32_e32 v140, v4
	v_mov_b32_e32 v141, v4
	v_mov_b32_e32 v142, v4
	v_mov_b32_e32 v143, v4
	v_mov_b32_e32 v144, v4
	v_mov_b32_e32 v145, v4
	v_mov_b32_e32 v146, v4
	v_mov_b32_e32 v147, v4
	.p2align	6

;     __device__ __forceinline__ bool next(int i, Unit& u) const { if (i >= n) return false; u.pm = pm; u.pn = pn0 + i; return true; }
;     __device__ __forceinline__ bool next(int i, Unit& u) const { if (i) return false; u.pm = pm; u.pn = pn; return true; }
;     ...
;         const bool has_next = S.next(ui + 1, nxt);
;         const char* nA = has_next ? (const char*)g.A + (size_t)nxt.pm * tstep : cA; const char* nB = has_next ? (const char*)g.Bt + (size_t)nxt.pn * tstep : cB;
;         for (int t = 0; t < nt; t += 2) {
;             const bool last = (t == nt - 2);
;             const char* a1 = cA + (size_t)(t + 1) * kstep;
;             const char* a2 = last ? nA : cA + (size_t)(t + 2) * kstep; const char* b2 = last ? nB : cB + (size_t)(t + 2) * kstep;
;             const char* a3 = a2 + kstep; const char* b3 = b2 + kstep;
;     ...
; #pragma unroll
;         for (int a = 0; a < 2; ++a)
; #pragma unroll
;             for (int b = 0; b < 2; ++b)
; #pragma unroll
;                 for (int m = 0; m < 4; ++m)
; #pragma unroll
;                     for (int n = 0; n < 2; ++n) acc[a][b][m][n] = (f32x4){0.f, 0.f, 0.f, 0.f};
;         cur = nxt; cA = nA; cB = nB; ++ui;
.LBB0_752:
	s_ashr_i32 s61, s60, 31
	s_lshl_b64 s[54:55], s[60:61], 20
	s_add_u32 s62, s36, s54
	s_addc_u32 s63, s37, s55
	s_and_b64 s[54:55], s[8:9], exec
	s_cselect_b32 s53, s63, s69
	s_cselect_b32 s54, s62, s68
	s_ashr_i32 s25, s24, 31
	s_lshl_b64 s[58:59], s[24:25], 20
	s_add_u32 s70, s81, s58
	s_addc_u32 s71, s6, s59
	s_and_b64 s[58:59], s[8:9], exec
	s_cselect_b32 s25, s71, s77
	s_cselect_b32 s55, s70, s76
	s_add_u32 s68, s68, 0x80080
	s_addc_u32 s69, s69, 0
	s_add_u32 s56, s76, 0x100
	v_mov_b32_e32 v4, 0
	s_addc_u32 s58, s77, 0
	s_mov_b32 s59, -2
	v_mov_b32_e32 v5, v4
	v_mov_b32_e32 v6, v4
	v_mov_b32_e32 v7, v4
	v_mov_b32_e32 v8, v4
	v_mov_b32_e32 v9, v4
	v_mov_b32_e32 v10, v4
	v_mov_b32_e32 v11, v4
	v_mov_b32_e32 v16, v4
	v_mov_b32_e32 v17, v4
	v_mov_b32_e32 v18, v4
	v_mov_b32_e32 v19, v4
	s_waitcnt vmcnt(0)
	v_mov_b32_e32 v24, v4
	v_mov_b32_e32 v25, v4
	v_mov_b32_e32 v26, v4
	v_mov_b32_e32 v27, v4
	v_mov_b32_e32 v32, v4
	v_mov_b32_e32 v33, v4
	v_mov_b32_e32 v34, v4
	v_mov_b32_e32 v35, v4
	v_mov_b32_e32 v40, v4
	v_mov_b32_e32 v41, v4
	v_mov_b32_e32 v42, v4
	v_mov_b32_e32 v43, v4
	v_mov_b32_e32 v48, v4
	v_mov_b32_e32 v49, v4
	v_mov_b32_e32 v50, v4
	v_mov_b32_e32 v51, v4
	v_mov_b32_e32 v56, v4
	v_mov_b32_e32 v57, v4
	v_mov_b32_e32 v58, v4
	v_mov_b32_e32 v59, v4
	v_mov_b32_e32 v12, v4
	v_mov_b32_e32 v13, v4
	v_mov_b32_e32 v14, v4
	v_mov_b32_e32 v15, v4
	v_mov_b32_e32 v20, v4
	v_mov_b32_e32 v21, v4
	v_mov_b32_e32 v22, v4
	v_mov_b32_e32 v23, v4
	v_mov_b32_e32 v28, v4
	v_mov_b32_e32 v29, v4
	v_mov_b32_e32 v30, v4
	v_mov_b32_e32 v31, v4
	v_mov_b32_e32 v36, v4
	v_mov_b32_e32 v37, v4
	v_mov_b32_e32 v38, v4
	v_mov_b32_e32 v39, v4
	v_mov_b32_e32 v44, v4
	v_mov_b32_e32 v45, v4
	v_mov_b32_e32 v46, v4
	v_mov_b32_e32 v47, v4
	v_mov_b32_e32 v52, v4
	v_mov_b32_e32 v53, v4
	v_mov_b32_e32 v54, v4
	v_mov_b32_e32 v55, v4
	v_mov_b32_e32 v60, v4
	v_mov_b32_e32 v61, v4
	v_mov_b32_e32 v62, v4
	v_mov_b32_e32 v63, v4
	v_mov_b32_e32 v64, v4
	v_mov_b32_e32 v65, v4
	v_mov_b32_e32 v66, v4
	v_mov_b32_e32 v67, v4
	v_mov_b32_e32 v68, v4
	v_mov_b32_e32 v69, v4
	v_mov_b32_e32 v70, v4
	v_mov_b32_e32 v71, v4
	v_mov_b32_e32 v72, v4
	v_mov_b32_e32 v73, v4
	v_mov_b32_e32 v74, v4
	v_mov_b32_e32 v75, v4
	v_mov_b32_e32 v80, v4
	v_mov_b32_e32 v81, v4
	v_mov_b32_e32 v82, v4
	v_mov_b32_e32 v83, v4
	v_mov_b32_e32 v88, v4
	v_mov_b32_e32 v89, v4
	v_mov_b32_e32 v90, v4
	v_mov_b32_e32 v91, v4
	v_mov_b32_e32 v96, v4
	v_mov_b32_e32 v97, v4
	v_mov_b32_e32 v98, v4
	v_mov_b32_e32 v99, v4
	v_mov_b32_e32 v104, v4
	v_mov_b32_e32 v105, v4
	v_mov_b32_e32 v106, v4
	v_mov_b32_e32 v107, v4
	v_mov_b32_e32 v112, v4
	v_mov_b32_e32 v113, v4
	v_mov_b32_e32 v114, v4
	v_mov_b32_e32 v115, v4
	v_mov_b32_e32 v120, v4
	v_mov_b32_e32 v121, v4
	v_mov_b32_e32 v122, v4
	v_mov_b32_e32 v123, v4
	v_mov_b32_e32 v76, v4
	v_mov_b32_e32 v77, v4
	v_mov_b32_e32 v78, v4
	v_mov_b32_e32 v79, v4
	v_mov_b32_e32 v84, v4
	v_mov_b32_e32 v85, v4
	v_mov_b32_e32 v86, v4
	v_mov_b32_e32 v87, v4
	v_mov_b32_e32 v92, v4
	v_mov_b32_e32 v93, v4
	v_mov_b32_e32 v94, v4
	v_mov_b32_e32 v95, v4
	v_mov_b32_e32 v100, v4
	v_mov_b32_e32 v101, v4
	v_mov_b32_e32 v102, v4
	v_mov_b32_e32 v103, v4
	v_mov_b32_e32 v108, v4
	v_mov_b32_e32 v109, v4
	v_mov_b32_e32 v110, v4
	v_mov_b32_e32 v111, v4
	v_mov_b32_e32 v116, v4
	v_mov_b32_e32 v117, v4
	v_mov_b32_e32 v118, v4
	v_mov_b32_e32 v119, v4
	v_mov_b32_e32 v124, v4
	v_mov_b32_e32 v125, v4
	v_mov_b32_e32 v126, v4
	v_mov_b32_e32 v127, v4
	v_mov_b32_e32 v128, v4
	v_mov_b32_e32 v129, v4
	v_mov_b32_e32 v130, v4
	v_mov_b32_e32 v131, v4
	s_waitcnt lgkmcnt(0)
	.p2align	6

;     __device__ __forceinline__ bool next(int i, Unit& u) const { if (i >= n) return false; u.pm = pm; u.pn = pn0 + i; return true; }
;     __device__ __forceinline__ bool next(int i, Unit& u) const { if (i) return false; u.pm = pm; u.pn = pn; return true; }
;     ...
;         const bool has_next = S.next(ui + 1, nxt);
;         const char* nA = has_next ? (const char*)g.A + (size_t)nxt.pm * tstep : cA; const char* nB = has_next ? (const char*)g.Bt + (size_t)nxt.pn * tstep : cB;
;         for (int t = 0; t < nt; t += 2) {
;             const bool last = (t == nt - 2);
;             const char* a1 = cA + (size_t)(t + 1) * kstep;
;             const char* a2 = last ? nA : cA + (size_t)(t + 2) * kstep; const char* b2 = last ? nB : cB + (size_t)(t + 2) * kstep;
;             const char* a3 = a2 + kstep; const char* b3 = b2 + kstep;
;     ...
; #pragma unroll
;         for (int a = 0; a < 2; ++a)
; #pragma unroll
;             for (int b = 0; b < 2; ++b)
; #pragma unroll
;                 for (int m = 0; m < 4; ++m)
; #pragma unroll
;                     for (int n = 0; n < 2; ++n) acc[a][b][m][n] = (f32x4){0.f, 0.f, 0.f, 0.f};
;         cur = nxt; cA = nA; cB = nB; ++ui;
.LBB0_997:
	s_ashr_i32 s51, s50, 31
	s_lshl_b64 s[60:61], s[50:51], 20
	s_add_u32 s60, s7, s60
	s_addc_u32 s61, s82, s61
	s_and_b64 s[62:63], s[8:9], exec
	s_cselect_b32 s51, s61, s71
	s_cselect_b32 s59, s60, s70
	s_ashr_i32 s25, s24, 31
	s_lshl_b64 s[62:63], s[24:25], 20
	s_add_u32 s62, s1, s62
	s_addc_u32 s63, s4, s63
	s_and_b64 s[76:77], s[8:9], exec
	s_cselect_b32 s25, s63, s69
	s_cselect_b32 s73, s62, s68
	s_add_u32 s75, s68, 0x100
	s_addc_u32 s78, s69, 0
	s_add_u32 s68, s70, 0x80080
	v_mov_b32_e32 v4, 0
	s_addc_u32 s69, s71, 0
	s_mov_b32 s79, -2
	v_mov_b32_e32 v5, v4
	v_mov_b32_e32 v6, v4
	v_mov_b32_e32 v7, v4
	v_mov_b32_e32 v8, v4
	v_mov_b32_e32 v9, v4
	v_mov_b32_e32 v10, v4
	v_mov_b32_e32 v11, v4
	v_mov_b32_e32 v20, v4
	v_mov_b32_e32 v21, v4
	v_mov_b32_e32 v22, v4
	v_mov_b32_e32 v23, v4
	v_mov_b32_e32 v24, v4
	v_mov_b32_e32 v25, v4
	v_mov_b32_e32 v26, v4
	v_mov_b32_e32 v27, v4
	v_mov_b32_e32 v36, v4
	v_mov_b32_e32 v37, v4
	v_mov_b32_e32 v38, v4
	v_mov_b32_e32 v39, v4
	v_mov_b32_e32 v40, v4
	v_mov_b32_e32 v41, v4
	v_mov_b32_e32 v42, v4
	v_mov_b32_e32 v43, v4
	v_mov_b32_e32 v52, v4
	v_mov_b32_e32 v53, v4
	v_mov_b32_e32 v54, v4
	v_mov_b32_e32 v55, v4
	v_mov_b32_e32 v56, v4
	v_mov_b32_e32 v57, v4
	v_mov_b32_e32 v58, v4
	v_mov_b32_e32 v59, v4
	v_mov_b32_e32 v12, v4
	v_mov_b32_e32 v13, v4
	v_mov_b32_e32 v14, v4
	v_mov_b32_e32 v15, v4
	v_mov_b32_e32 v16, v4
	v_mov_b32_e32 v17, v4
	v_mov_b32_e32 v18, v4
	v_mov_b32_e32 v19, v4
	v_mov_b32_e32 v28, v4
	v_mov_b32_e32 v29, v4
	v_mov_b32_e32 v30, v4
	v_mov_b32_e32 v31, v4
	v_mov_b32_e32 v32, v4
	v_mov_b32_e32 v33, v4
	v_mov_b32_e32 v34, v4
	v_mov_b32_e32 v35, v4
	v_mov_b32_e32 v44, v4
	v_mov_b32_e32 v45, v4
	v_mov_b32_e32 v46, v4
	v_mov_b32_e32 v47, v4
	v_mov_b32_e32 v48, v4
	v_mov_b32_e32 v49, v4
	v_mov_b32_e32 v50, v4
	v_mov_b32_e32 v51, v4
	v_mov_b32_e32 v60, v4
	v_mov_b32_e32 v61, v4
	v_mov_b32_e32 v62, v4
	v_mov_b32_e32 v63, v4
	v_mov_b32_e32 v64, v4
	v_mov_b32_e32 v65, v4
	v_mov_b32_e32 v66, v4
	v_mov_b32_e32 v67, v4
	v_mov_b32_e32 v68, v4
	v_mov_b32_e32 v69, v4
	v_mov_b32_e32 v70, v4
	v_mov_b32_e32 v71, v4
	v_mov_b32_e32 v72, v4
	v_mov_b32_e32 v73, v4
	v_mov_b32_e32 v74, v4
	v_mov_b32_e32 v75, v4
	v_mov_b32_e32 v84, v4
	v_mov_b32_e32 v85, v4
	v_mov_b32_e32 v86, v4
	v_mov_b32_e32 v87, v4
	v_mov_b32_e32 v88, v4
	v_mov_b32_e32 v89, v4
	v_mov_b32_e32 v90, v4
	v_mov_b32_e32 v91, v4
	v_mov_b32_e32 v100, v4
	v_mov_b32_e32 v101, v4
	v_mov_b32_e32 v102, v4
	v_mov_b32_e32 v103, v4
	v_mov_b32_e32 v104, v4
	v_mov_b32_e32 v105, v4
	v_mov_b32_e32 v106, v4
	v_mov_b32_e32 v107, v4
	v_mov_b32_e32 v124, v4
	v_mov_b32_e32 v125, v4
	v_mov_b32_e32 v126, v4
	v_mov_b32_e32 v127, v4
	v_mov_b32_e32 v132, v4
	v_mov_b32_e32 v133, v4
	v_mov_b32_e32 v134, v4
	v_mov_b32_e32 v135, v4
	v_mov_b32_e32 v76, v4
	v_mov_b32_e32 v77, v4
	v_mov_b32_e32 v78, v4
	v_mov_b32_e32 v79, v4
	v_mov_b32_e32 v80, v4
	v_mov_b32_e32 v81, v4
	v_mov_b32_e32 v82, v4
	v_mov_b32_e32 v83, v4
	v_mov_b32_e32 v92, v4
	v_mov_b32_e32 v93, v4
	v_mov_b32_e32 v94, v4
	v_mov_b32_e32 v95, v4
	v_mov_b32_e32 v96, v4
	v_mov_b32_e32 v97, v4
	v_mov_b32_e32 v98, v4
	v_mov_b32_e32 v99, v4
	v_mov_b32_e32 v116, v4
	v_mov_b32_e32 v117, v4
	v_mov_b32_e32 v118, v4
	v_mov_b32_e32 v119, v4
	v_mov_b32_e32 v120, v4
	v_mov_b32_e32 v121, v4
	v_mov_b32_e32 v122, v4
	v_mov_b32_e32 v123, v4
	v_mov_b32_e32 v140, v4
	v_mov_b32_e32 v141, v4
	v_mov_b32_e32 v142, v4
	v_mov_b32_e32 v143, v4
	v_mov_b32_e32 v144, v4
	v_mov_b32_e32 v145, v4
	s_waitcnt vmcnt(0)
	v_mov_b32_e32 v146, v4
	v_mov_b32_e32 v147, v4
	.p2align	6

;     __device__ __forceinline__ bool next(int i, Unit& u) const { if (i >= n) return false; u.pm = pm; u.pn = pn0 + i; return true; }
;     __device__ __forceinline__ bool next(int i, Unit& u) const { if (i) return false; u.pm = pm; u.pn = pn; return true; }
;     ...
;         const bool has_next = S.next(ui + 1, nxt);
;         const char* nA = has_next ? (const char*)g.A + (size_t)nxt.pm * tstep : cA; const char* nB = has_next ? (const char*)g.Bt + (size_t)nxt.pn * tstep : cB;
;         for (int t = 0; t < nt; t += 2) {
;             const bool last = (t == nt - 2);
;             const char* a1 = cA + (size_t)(t + 1) * kstep;
;             const char* a2 = last ? nA : cA + (size_t)(t + 2) * kstep; const char* b2 = last ? nB : cB + (size_t)(t + 2) * kstep;
;             const char* a3 = a2 + kstep; const char* b3 = b2 + kstep;
;     ...
; #pragma unroll
;         for (int a = 0; a < 2; ++a)
; #pragma unroll
;             for (int b = 0; b < 2; ++b)
; #pragma unroll
;                 for (int m = 0; m < 4; ++m)
; #pragma unroll
;                     for (int n = 0; n < 2; ++n) acc[a][b][m][n] = (f32x4){0.f, 0.f, 0.f, 0.f};
;         cur = nxt; cA = nA; cB = nB; ++ui;
.LBB0_1085:
	s_ashr_i32 s97, s96, 31
	s_lshl_b64 s[12:13], s[96:97], 20
	s_add_u32 s90, s36, s12
	s_addc_u32 s91, s37, s13
	s_and_b64 s[12:13], s[6:7], exec
	s_cselect_b32 s69, s91, s9
	s_cselect_b32 s76, s90, s8
	s_ashr_i32 s89, s88, 31
	s_lshl_b64 s[12:13], s[88:89], 20
	s_add_u32 s94, s58, s12
	s_addc_u32 s95, s59, s13
	s_and_b64 s[12:13], s[6:7], exec
	s_cselect_b32 s77, s95, s11
	s_cselect_b32 s82, s94, s10
	s_add_u32 s8, s8, 0x80080
	s_addc_u32 s9, s9, 0
	s_add_u32 s83, s10, 0x100
	v_mov_b32_e32 v12, 0
	s_addc_u32 s89, s11, 0
	s_mov_b32 s97, -2
	v_mov_b32_e32 v13, v12
	v_mov_b32_e32 v14, v12
	v_mov_b32_e32 v15, v12
	v_mov_b32_e32 v16, v12
	v_mov_b32_e32 v17, v12
	v_mov_b32_e32 v18, v12
	v_mov_b32_e32 v19, v12
	v_mov_b32_e32 v24, v12
	v_mov_b32_e32 v25, v12
	v_mov_b32_e32 v26, v12
	v_mov_b32_e32 v27, v12
	v_mov_b32_e32 v84, v12
	v_mov_b32_e32 v85, v12
	v_mov_b32_e32 v86, v12
	v_mov_b32_e32 v87, v12
	v_mov_b32_e32 v28, v12
	v_mov_b32_e32 v29, v12
	v_mov_b32_e32 v30, v12
	v_mov_b32_e32 v31, v12
	v_mov_b32_e32 v88, v12
	v_mov_b32_e32 v89, v12
	v_mov_b32_e32 v90, v12
	v_mov_b32_e32 v91, v12
	v_mov_b32_e32 v32, v12
	v_mov_b32_e32 v33, v12
	v_mov_b32_e32 v34, v12
	v_mov_b32_e32 v35, v12
	v_mov_b32_e32 v102, v12
	v_mov_b32_e32 v103, v12
	v_mov_b32_e32 v104, v12
	v_mov_b32_e32 v105, v12
	v_mov_b32_e32 v20, v12
	v_mov_b32_e32 v21, v12
	v_mov_b32_e32 v22, v12
	v_mov_b32_e32 v23, v12
	v_mov_b32_e32 v80, v12
	v_mov_b32_e32 v81, v12
	v_mov_b32_e32 v82, v12
	v_mov_b32_e32 v83, v12
	v_mov_b32_e32 v36, v12
	v_mov_b32_e32 v37, v12
	v_mov_b32_e32 v38, v12
	v_mov_b32_e32 v39, v12
	v_mov_b32_e32 v138, v12
	v_mov_b32_e32 v139, v12
	v_mov_b32_e32 v140, v12
	v_mov_b32_e32 v141, v12
	v_mov_b32_e32 v40, v12
	v_mov_b32_e32 v41, v12
	v_mov_b32_e32 v42, v12
	v_mov_b32_e32 v43, v12
	v_mov_b32_e32 v142, v12
	v_mov_b32_e32 v143, v12
	v_mov_b32_e32 v144, v12
	v_mov_b32_e32 v145, v12
	v_mov_b32_e32 v44, v12
	v_mov_b32_e32 v45, v12
	v_mov_b32_e32 v46, v12
	v_mov_b32_e32 v47, v12
	v_mov_b32_e32 v146, v12
	v_mov_b32_e32 v147, v12
	v_mov_b32_e32 v148, v12
	v_mov_b32_e32 v149, v12
	v_mov_b32_e32 v68, v12
	v_mov_b32_e32 v69, v12
	v_mov_b32_e32 v70, v12
	v_mov_b32_e32 v71, v12
	v_mov_b32_e32 v92, v12
	v_mov_b32_e32 v93, v12
	v_mov_b32_e32 v94, v12
	v_mov_b32_e32 v95, v12
	v_mov_b32_e32 v48, v12
	v_mov_b32_e32 v49, v12
	v_mov_b32_e32 v50, v12
	v_mov_b32_e32 v51, v12
	v_mov_b32_e32 v150, v12
	v_mov_b32_e32 v151, v12
	v_mov_b32_e32 v152, v12
	v_mov_b32_e32 v153, v12
	v_mov_b32_e32 v52, v12
	v_mov_b32_e32 v53, v12
	v_mov_b32_e32 v54, v12
	v_mov_b32_e32 v55, v12
	v_mov_b32_e32 v154, v12
	v_mov_b32_e32 v155, v12
	v_mov_b32_e32 v156, v12
	v_mov_b32_e32 v157, v12
	v_mov_b32_e32 v64, v12
	v_mov_b32_e32 v65, v12
	v_mov_b32_e32 v66, v12
	v_mov_b32_e32 v67, v12
	v_mov_b32_e32 v8, v12
	v_mov_b32_e32 v9, v12
	v_mov_b32_e32 v10, v12
	v_mov_b32_e32 v11, v12
	v_mov_b32_e32 v76, v12
	v_mov_b32_e32 v77, v12
	v_mov_b32_e32 v78, v12
	v_mov_b32_e32 v79, v12
	v_mov_b32_e32 v96, v12
	v_mov_b32_e32 v97, v12
	v_mov_b32_e32 v98, v12
	v_mov_b32_e32 v99, v12
	v_mov_b32_e32 v56, v12
	v_mov_b32_e32 v57, v12
	v_mov_b32_e32 v58, v12
	v_mov_b32_e32 v59, v12
	v_mov_b32_e32 v158, v12
	v_mov_b32_e32 v159, v12
	v_mov_b32_e32 v160, v12
	v_mov_b32_e32 v161, v12
	v_mov_b32_e32 v60, v12
	v_mov_b32_e32 v61, v12
	v_mov_b32_e32 v62, v12
	v_mov_b32_e32 v63, v12
	v_mov_b32_e32 v162, v12
	v_mov_b32_e32 v163, v12
	v_mov_b32_e32 v164, v12
	v_mov_b32_e32 v165, v12
	v_mov_b32_e32 v72, v12
	v_mov_b32_e32 v73, v12
	v_mov_b32_e32 v74, v12
	v_mov_b32_e32 v75, v12
	v_mov_b32_e32 v4, v12
	v_mov_b32_e32 v5, v12
	v_mov_b32_e32 v6, v12
	v_mov_b32_e32 v7, v12
	.p2align	6

;     ...
; #pragma unroll
;         for (int a = 0; a < 2; ++a)
; #pragma unroll
;             for (int b = 0; b < 2; ++b)
; #pragma unroll
;                 for (int m = 0; m < 4; ++m)
; #pragma unroll
;                     for (int n = 0; n < 2; ++n) acc[a][b][m][n] = (f32x4){0.f, 0.f, 0.f, 0.f};
;         cur = nxt; cA = nA; cB = nB; ++ui;
.LBB0_1211:
	s_add_u32 s77, s62, 0x100
	v_mov_b32_e32 v4, 0
	s_addc_u32 s78, s63, 0
	s_mov_b32 s79, -2
	v_mov_b32_e32 v5, v4
	v_mov_b32_e32 v6, v4
	v_mov_b32_e32 v7, v4
	v_mov_b32_e32 v8, v4
	v_mov_b32_e32 v9, v4
	v_mov_b32_e32 v10, v4
	v_mov_b32_e32 v11, v4
	v_mov_b32_e32 v20, v4
	v_mov_b32_e32 v21, v4
	v_mov_b32_e32 v22, v4
	v_mov_b32_e32 v23, v4
	s_waitcnt vmcnt(0)
	v_mov_b32_e32 v24, v4
	v_mov_b32_e32 v25, v4
	v_mov_b32_e32 v26, v4
	v_mov_b32_e32 v27, v4
	v_mov_b32_e32 v36, v4
	v_mov_b32_e32 v37, v4
	v_mov_b32_e32 v38, v4
	v_mov_b32_e32 v39, v4
	v_mov_b32_e32 v40, v4
	v_mov_b32_e32 v41, v4
	v_mov_b32_e32 v42, v4
	v_mov_b32_e32 v43, v4
	v_mov_b32_e32 v52, v4
	v_mov_b32_e32 v53, v4
	v_mov_b32_e32 v54, v4
	v_mov_b32_e32 v55, v4
	v_mov_b32_e32 v56, v4
	v_mov_b32_e32 v57, v4
	v_mov_b32_e32 v58, v4
	v_mov_b32_e32 v59, v4
	v_mov_b32_e32 v12, v4
	v_mov_b32_e32 v13, v4
	v_mov_b32_e32 v14, v4
	v_mov_b32_e32 v15, v4
	v_mov_b32_e32 v16, v4
	v_mov_b32_e32 v17, v4
	v_mov_b32_e32 v18, v4
	v_mov_b32_e32 v19, v4
	v_mov_b32_e32 v28, v4
	v_mov_b32_e32 v29, v4
	v_mov_b32_e32 v30, v4
	v_mov_b32_e32 v31, v4
	v_mov_b32_e32 v32, v4
	v_mov_b32_e32 v33, v4
	v_mov_b32_e32 v34, v4
	v_mov_b32_e32 v35, v4
	v_mov_b32_e32 v44, v4
	v_mov_b32_e32 v45, v4
	v_mov_b32_e32 v46, v4
	v_mov_b32_e32 v47, v4
	v_mov_b32_e32 v48, v4
	v_mov_b32_e32 v49, v4
	v_mov_b32_e32 v50, v4
	v_mov_b32_e32 v51, v4
	v_mov_b32_e32 v60, v4
	v_mov_b32_e32 v61, v4
	v_mov_b32_e32 v62, v4
	v_mov_b32_e32 v63, v4
	v_mov_b32_e32 v64, v4
	v_mov_b32_e32 v65, v4
	v_mov_b32_e32 v66, v4
	v_mov_b32_e32 v67, v4
	v_mov_b32_e32 v68, v4
	v_mov_b32_e32 v69, v4
	v_mov_b32_e32 v70, v4
	v_mov_b32_e32 v71, v4
	v_mov_b32_e32 v72, v4
	v_mov_b32_e32 v73, v4
	v_mov_b32_e32 v74, v4
	v_mov_b32_e32 v75, v4
	v_mov_b32_e32 v84, v4
	v_mov_b32_e32 v85, v4
	v_mov_b32_e32 v86, v4
	v_mov_b32_e32 v87, v4
	v_mov_b32_e32 v88, v4
	v_mov_b32_e32 v89, v4
	v_mov_b32_e32 v90, v4
	v_mov_b32_e32 v91, v4
	v_mov_b32_e32 v100, v4
	v_mov_b32_e32 v101, v4
	v_mov_b32_e32 v102, v4
	v_mov_b32_e32 v103, v4
	v_mov_b32_e32 v104, v4
	v_mov_b32_e32 v105, v4
	v_mov_b32_e32 v106, v4
	v_mov_b32_e32 v107, v4
	v_mov_b32_e32 v124, v4
	v_mov_b32_e32 v125, v4
	v_mov_b32_e32 v126, v4
	v_mov_b32_e32 v127, v4
	v_mov_b32_e32 v132, v4
	v_mov_b32_e32 v133, v4
	v_mov_b32_e32 v134, v4
	v_mov_b32_e32 v135, v4
	v_mov_b32_e32 v76, v4
	v_mov_b32_e32 v77, v4
	v_mov_b32_e32 v78, v4
	v_mov_b32_e32 v79, v4
	v_mov_b32_e32 v80, v4
	v_mov_b32_e32 v81, v4
	v_mov_b32_e32 v82, v4
	v_mov_b32_e32 v83, v4
	v_mov_b32_e32 v92, v4
	v_mov_b32_e32 v93, v4
	v_mov_b32_e32 v94, v4
	v_mov_b32_e32 v95, v4
	v_mov_b32_e32 v96, v4
	v_mov_b32_e32 v97, v4
	v_mov_b32_e32 v98, v4
	v_mov_b32_e32 v99, v4
	v_mov_b32_e32 v116, v4
	v_mov_b32_e32 v117, v4
	v_mov_b32_e32 v118, v4
	v_mov_b32_e32 v119, v4
	v_mov_b32_e32 v120, v4
	v_mov_b32_e32 v121, v4
	v_mov_b32_e32 v122, v4
	v_mov_b32_e32 v123, v4
	v_mov_b32_e32 v140, v4
	v_mov_b32_e32 v141, v4
	v_mov_b32_e32 v142, v4
	v_mov_b32_e32 v143, v4
	v_mov_b32_e32 v144, v4
	v_mov_b32_e32 v145, v4
	v_mov_b32_e32 v146, v4
	v_mov_b32_e32 v147, v4
	.p2align	6

;     ...
; #pragma unroll
;         for (int a = 0; a < 2; ++a)
; #pragma unroll
;             for (int b = 0; b < 2; ++b)
; #pragma unroll
;                 for (int m = 0; m < 4; ++m)
; #pragma unroll
;                     for (int n = 0; n < 2; ++n) acc[a][b][m][n] = (f32x4){0.f, 0.f, 0.f, 0.f};
;         cur = nxt; cA = nA; cB = nB; ++ui;
.LBB0_1253:
	s_add_u32 s75, s60, 0x100
	v_mov_b32_e32 v4, 0
	s_addc_u32 s76, s61, 0
	s_mov_b32 s77, -2
	v_mov_b32_e32 v5, v4
	v_mov_b32_e32 v6, v4
	v_mov_b32_e32 v7, v4
	v_mov_b32_e32 v8, v4
	v_mov_b32_e32 v9, v4
	v_mov_b32_e32 v10, v4
	v_mov_b32_e32 v11, v4
	v_mov_b32_e32 v20, v4
	v_mov_b32_e32 v21, v4
	v_mov_b32_e32 v22, v4
	v_mov_b32_e32 v23, v4
	s_waitcnt vmcnt(0)
	v_mov_b32_e32 v24, v4
	v_mov_b32_e32 v25, v4
	v_mov_b32_e32 v26, v4
	v_mov_b32_e32 v27, v4
	v_mov_b32_e32 v36, v4
	v_mov_b32_e32 v37, v4
	v_mov_b32_e32 v38, v4
	v_mov_b32_e32 v39, v4
	v_mov_b32_e32 v40, v4
	v_mov_b32_e32 v41, v4
	v_mov_b32_e32 v42, v4
	v_mov_b32_e32 v43, v4
	v_mov_b32_e32 v52, v4
	v_mov_b32_e32 v53, v4
	v_mov_b32_e32 v54, v4
	v_mov_b32_e32 v55, v4
	v_mov_b32_e32 v56, v4
	v_mov_b32_e32 v57, v4
	v_mov_b32_e32 v58, v4
	v_mov_b32_e32 v59, v4
	v_mov_b32_e32 v12, v4
	v_mov_b32_e32 v13, v4
	v_mov_b32_e32 v14, v4
	v_mov_b32_e32 v15, v4
	v_mov_b32_e32 v16, v4
	v_mov_b32_e32 v17, v4
	v_mov_b32_e32 v18, v4
	v_mov_b32_e32 v19, v4
	v_mov_b32_e32 v28, v4
	v_mov_b32_e32 v29, v4
	v_mov_b32_e32 v30, v4
	v_mov_b32_e32 v31, v4
	v_mov_b32_e32 v32, v4
	v_mov_b32_e32 v33, v4
	v_mov_b32_e32 v34, v4
	v_mov_b32_e32 v35, v4
	v_mov_b32_e32 v44, v4
	v_mov_b32_e32 v45, v4
	v_mov_b32_e32 v46, v4
	v_mov_b32_e32 v47, v4
	v_mov_b32_e32 v48, v4
	v_mov_b32_e32 v49, v4
	v_mov_b32_e32 v50, v4
	v_mov_b32_e32 v51, v4
	v_mov_b32_e32 v60, v4
	v_mov_b32_e32 v61, v4
	v_mov_b32_e32 v62, v4
	v_mov_b32_e32 v63, v4
	v_mov_b32_e32 v64, v4
	v_mov_b32_e32 v65, v4
	v_mov_b32_e32 v66, v4
	v_mov_b32_e32 v67, v4
	v_mov_b32_e32 v68, v4
	v_mov_b32_e32 v69, v4
	v_mov_b32_e32 v70, v4
	v_mov_b32_e32 v71, v4
	v_mov_b32_e32 v72, v4
	v_mov_b32_e32 v73, v4
	v_mov_b32_e32 v74, v4
	v_mov_b32_e32 v75, v4
	v_mov_b32_e32 v84, v4
	v_mov_b32_e32 v85, v4
	v_mov_b32_e32 v86, v4
	v_mov_b32_e32 v87, v4
	v_mov_b32_e32 v88, v4
	v_mov_b32_e32 v89, v4
	v_mov_b32_e32 v90, v4
	v_mov_b32_e32 v91, v4
	v_mov_b32_e32 v100, v4
	v_mov_b32_e32 v101, v4
	v_mov_b32_e32 v102, v4
	v_mov_b32_e32 v103, v4
	v_mov_b32_e32 v104, v4
	v_mov_b32_e32 v105, v4
	v_mov_b32_e32 v106, v4
	v_mov_b32_e32 v107, v4
	v_mov_b32_e32 v124, v4
	v_mov_b32_e32 v125, v4
	v_mov_b32_e32 v126, v4
	v_mov_b32_e32 v127, v4
	v_mov_b32_e32 v132, v4
	v_mov_b32_e32 v133, v4
	v_mov_b32_e32 v134, v4
	v_mov_b32_e32 v135, v4
	v_mov_b32_e32 v76, v4
	v_mov_b32_e32 v77, v4
	v_mov_b32_e32 v78, v4
	v_mov_b32_e32 v79, v4
	v_mov_b32_e32 v80, v4
	v_mov_b32_e32 v81, v4
	v_mov_b32_e32 v82, v4
	v_mov_b32_e32 v83, v4
	v_mov_b32_e32 v92, v4
	v_mov_b32_e32 v93, v4
	v_mov_b32_e32 v94, v4
	v_mov_b32_e32 v95, v4
	v_mov_b32_e32 v96, v4
	v_mov_b32_e32 v97, v4
	v_mov_b32_e32 v98, v4
	v_mov_b32_e32 v99, v4
	v_mov_b32_e32 v116, v4
	v_mov_b32_e32 v117, v4
	v_mov_b32_e32 v118, v4
	v_mov_b32_e32 v119, v4
	v_mov_b32_e32 v120, v4
	v_mov_b32_e32 v121, v4
	v_mov_b32_e32 v122, v4
	v_mov_b32_e32 v123, v4
	v_mov_b32_e32 v140, v4
	v_mov_b32_e32 v141, v4
	v_mov_b32_e32 v142, v4
	v_mov_b32_e32 v143, v4
	v_mov_b32_e32 v144, v4
	v_mov_b32_e32 v145, v4
	v_mov_b32_e32 v146, v4
	v_mov_b32_e32 v147, v4
	.p2align	6
